# baseline (speedup 1.0000x reference)
; template <int MODE> ...
;     ...
;       const bool active = (k32 <= w_last) && (w_first < L);
;       SPHASE(sub, active);
.LBB0_350:
	s_sub_i32 s8, s14, 31
	v_cmp_le_i32_e32 vcc, s8, v167
	s_and_b64 s[10:11], s[6:7], vcc
	s_and_saveexec_b64 s[8:9], s[10:11]
	s_cbranch_execz .LBB0_352
	ds_read_b128 v[2:5], v204 offset:512
	ds_read_b128 v[190:193], v204 offset:2592
	ds_read_b128 v[222:225], v204 offset:4672
	ds_read_b128 v[226:229], v204 offset:6752
	ds_read_b128 v[230:233], v204 offset:8832
	ds_read_b128 v[234:237], v204 offset:10912
	ds_read_b128 v[238:241], v204 offset:12992
	ds_read_b128 v[242:245], v204 offset:15072
	ds_read_b128 v[246:249], v204 offset:17152
	s_waitcnt vmcnt(16) lgkmcnt(8)
	v_mfma_f32_32x32x16_bf16 v[2:17], v[2:5], v[18:21], 0
	s_waitcnt vmcnt(15) lgkmcnt(7)
	v_mfma_f32_32x32x16_bf16 v[2:17], v[190:193], v[22:25], v[2:17]
	ds_read_b128 v[190:193], v204 offset:19232
	s_waitcnt vmcnt(14) lgkmcnt(7)
	v_mfma_f32_32x32x16_bf16 v[2:17], v[222:225], v[26:29], v[2:17]
	ds_read_b128 v[222:225], v204 offset:21312
	s_waitcnt vmcnt(13) lgkmcnt(7)
	v_mfma_f32_32x32x16_bf16 v[2:17], v[226:229], v[96:99], v[2:17]
	ds_read_b128 v[226:229], v204 offset:23392
	s_waitcnt vmcnt(12) lgkmcnt(7)
	v_mfma_f32_32x32x16_bf16 v[2:17], v[230:233], v[100:103], v[2:17]
	s_waitcnt vmcnt(11) lgkmcnt(6)
	v_mfma_f32_32x32x16_bf16 v[2:17], v[234:237], v[104:107], v[2:17]
	s_waitcnt vmcnt(10) lgkmcnt(5)
	v_mfma_f32_32x32x16_bf16 v[2:17], v[238:241], v[108:111], v[2:17]
	s_waitcnt vmcnt(9) lgkmcnt(4)
	v_mfma_f32_32x32x16_bf16 v[2:17], v[242:245], v[112:115], v[2:17]
	s_waitcnt vmcnt(8) lgkmcnt(3)
	v_mfma_f32_32x32x16_bf16 v[2:17], v[246:249], v[116:119], v[2:17]
	s_waitcnt vmcnt(7) lgkmcnt(2)
	v_mfma_f32_32x32x16_bf16 v[2:17], v[190:193], v[120:123], v[2:17]
	s_waitcnt vmcnt(6) lgkmcnt(1)
	v_mfma_f32_32x32x16_bf16 v[2:17], v[222:225], v[124:127], v[2:17]
	s_waitcnt vmcnt(5) lgkmcnt(0)
	v_mfma_f32_32x32x16_bf16 v[2:17], v[226:229], v[128:131], v[2:17]

; template <int MODE> ...
;     ...
;       const bool active = (k32 <= w_last) && (w_first < L);
;       SPHASE(sub, active);
.LBB0_360:
	s_or_b64 exec, exec, s[8:9]
	s_sub_i32 s8, s14, 63
	v_cmp_le_i32_e32 vcc, s8, v167
	s_and_b64 s[10:11], s[6:7], vcc
	s_and_saveexec_b64 s[8:9], s[10:11]
	s_cbranch_execz .LBB0_362
	s_nop 1
	ds_read_b128 v[2:5], v204
	ds_read_b128 v[190:193], v204 offset:2080
	ds_read_b128 v[222:225], v204 offset:4160
	ds_read_b128 v[226:229], v204 offset:6240
	ds_read_b128 v[230:233], v204 offset:8320
	ds_read_b128 v[234:237], v204 offset:10400
	ds_read_b128 v[238:241], v204 offset:12480
	ds_read_b128 v[242:245], v204 offset:14560
	ds_read_b128 v[246:249], v204 offset:16640
	s_waitcnt vmcnt(16) lgkmcnt(8)
	v_mfma_f32_32x32x16_bf16 v[2:17], v[2:5], v[18:21], 0
	s_waitcnt vmcnt(15) lgkmcnt(7)
	v_mfma_f32_32x32x16_bf16 v[2:17], v[190:193], v[22:25], v[2:17]
	ds_read_b128 v[190:193], v204 offset:18720
	s_waitcnt vmcnt(14) lgkmcnt(7)
	v_mfma_f32_32x32x16_bf16 v[2:17], v[222:225], v[26:29], v[2:17]
	ds_read_b128 v[222:225], v204 offset:20800
	s_waitcnt vmcnt(13) lgkmcnt(7)
	v_mfma_f32_32x32x16_bf16 v[2:17], v[226:229], v[96:99], v[2:17]
	ds_read_b128 v[226:229], v204 offset:22880
	s_waitcnt vmcnt(12) lgkmcnt(7)
	v_mfma_f32_32x32x16_bf16 v[2:17], v[230:233], v[100:103], v[2:17]
	s_waitcnt vmcnt(11) lgkmcnt(6)
	v_mfma_f32_32x32x16_bf16 v[2:17], v[234:237], v[104:107], v[2:17]
	s_waitcnt vmcnt(10) lgkmcnt(5)
	v_mfma_f32_32x32x16_bf16 v[2:17], v[238:241], v[108:111], v[2:17]
	s_waitcnt vmcnt(9) lgkmcnt(4)
	v_mfma_f32_32x32x16_bf16 v[2:17], v[242:245], v[112:115], v[2:17]
	s_waitcnt vmcnt(8) lgkmcnt(3)
	v_mfma_f32_32x32x16_bf16 v[2:17], v[246:249], v[116:119], v[2:17]
	s_waitcnt vmcnt(7) lgkmcnt(2)
	v_mfma_f32_32x32x16_bf16 v[2:17], v[190:193], v[120:123], v[2:17]
	s_waitcnt vmcnt(6) lgkmcnt(1)
	v_mfma_f32_32x32x16_bf16 v[2:17], v[222:225], v[124:127], v[2:17]
	s_waitcnt vmcnt(5) lgkmcnt(0)
	v_mfma_f32_32x32x16_bf16 v[2:17], v[226:229], v[128:131], v[2:17]

; template <int MODE> ...
;     ...
;     __syncthreads();
;     vcur ^= 1;
.LBB0_364:
	v_xor_b32_e32 v31, 0x10000, v31
	v_xor_b32_e32 v204, 0x10000, v204
	s_cmp_lt_u32 s13, 2
	s_cbranch_scc1 .LBB0_366
	s_add_i32 s74, s14, 0xffffff41
	s_lshl_b64 s[8:9], s[74:75], 11
	s_waitcnt vmcnt(3)
	v_lshl_add_u64 v[136:137], v[156:157], 0, s[8:9]
	s_lshl_b64 s[8:9], s[74:75], 7
	s_waitcnt vmcnt(2)
	v_lshl_add_u64 v[140:141], v[158:159], 0, s[8:9]
	s_lshl_b64 s[8:9], s[74:75], 1
	s_waitcnt vmcnt(1)
	v_lshl_add_u64 v[144:145], v[160:161], 0, s[8:9]
	s_waitcnt vmcnt(0)
	v_lshl_add_u64 v[148:149], v[162:163], 0, s[8:9]
	global_load_dwordx4 v[132:135], v[136:137], off
	s_nop 0
	global_load_dwordx4 v[136:139], v[136:137], off offset:128
	s_nop 0
	global_load_dwordx4 v[140:143], v[140:141], off
	s_nop 0
	global_load_dwordx4 v[144:147], v[144:145], off
	s_nop 0
	global_load_dwordx4 v[148:151], v[148:149], off
